# P2a tile schedule: 32-tile blocks permuted (k <-> first GLU block) so every XCD parity runs one q/k, one GLU and one gate epilogue
# baseline (speedup 1.0000x reference)
;     __device__ __forceinline__ bool next(int i, pg8::Unit& u) const {
;         const int L = L0 + i * G + c; if (L >= L1) return false;
;         constexpr size_t RB = (size_t)DM * 2;
;         const char* H = ws + WS_H; const char* WT = ws + WS_WT;
;         if (L < 768) {
;             int wgid = (L % 8) * 96 + L / 8;
;             const int gid = wgid / 192, rem = wgid % 192;
;             const int pm = gid * 8 + (rem % 8), pn = rem / 8;
;             u.a = H + (size_t)(256 + 256 * pm) * RB; u.b = WT + (size_t)(256 * pn) * RB; u.pm = pm; u.pn = pn;
;             u.kind = (pn < 8) ? 0 : ((pn >= 12 && pn < 20) ? 2 : 1);
.LBB0_322:
	s_and_b64 vcc, exec, s[4:5]
	s_cbranch_vccz .LBB0_642
	s_load_dwordx2 s[14:15], s[0:1], 0xa8
	s_waitcnt lgkmcnt(0)
	s_cmpk_lt_i32 s2, 0x300
	s_cselect_b64 s[6:7], -1, 0
	s_cmpk_gt_i32 s2, 0x2ff
	v_readfirstlane_b32 s12, v220
	s_cbranch_scc1 .LBB0_325
	s_ashr_i32 s3, s2, 31
	s_lshr_b32 s3, s3, 29
	s_add_i32 s3, s2, s3
	s_and_b32 s4, s3, 0x7fffff8
	s_sub_i32 s4, s2, s4
	s_mulk_i32 s4, 0x60
	s_ashr_i32 s3, s3, 3
	s_add_i32 s4, s4, s3
	s_mul_hi_i32 s3, s4, 0x2aaaaaab
	s_lshr_b32 s5, s3, 31
	s_ashr_i32 s3, s3, 5
	s_add_i32 s3, s3, s5
	s_mul_i32 s5, s3, 0xc0
	s_sub_i32 s10, s4, s5
	s_lshr_b32 s4, s10, 5
	s_mul_i32 s4, s4, 3
	s_lshr_b32 s4, 0x2c298, s4
	s_and_b32 s4, s4, 7
	s_and_b32 s10, s10, 31
	s_lshl_b32 s4, s4, 5
	s_or_b32 s10, s10, s4
	s_bfe_u32 s4, s10, 0x3001c
	s_add_i32 s4, s10, s4
	s_sext_i32_i16 s5, s4
	s_and_b32 s4, s4, 0xfff8
	s_sub_i32 s4, s10, s4
	s_lshl_b32 s3, s3, 3
	s_sext_i32_i16 s4, s4
	s_add_i32 s64, s3, s4
	s_lshl_b32 s4, s64, 8
	s_ashr_i32 s65, s5, 3
	s_ashr_i32 s5, s4, 31
	s_lshl_b64 s[4:5], s[4:5], 12
	s_add_u32 s3, s14, s4
	s_addc_u32 s5, s15, s5
	s_add_u32 s4, s3, 0x2900000
	s_addc_u32 s5, s5, 0
	s_lshl_b32 s8, s65, 8
	s_ashr_i32 s9, s8, 31
	s_lshl_b64 s[8:9], s[8:9], 12
	s_add_u32 s3, s14, s8
	s_addc_u32 s8, s15, s9
	s_add_u32 s20, s3, 0x100000
	s_addc_u32 s21, s8, 0
	s_add_i32 s3, s10, 0xffffffa0
	s_cmp_lt_u32 s3, 64
	s_cselect_b32 s3, 2, 1
	s_cmp_gt_i32 s10, 63
	s_cselect_b32 s42, s3, 0
	s_andn2_b64 vcc, exec, s[6:7]
	s_cbranch_vccz .LBB0_326
	s_branch .LBB0_383

;     __device__ __forceinline__ bool next(int i, pg8::Unit& u) const {
;         const int L = L0 + i * G + c; if (L >= L1) return false;
;         constexpr size_t RB = (size_t)DM * 2;
;         const char* H = ws + WS_H; const char* WT = ws + WS_WT;
;         if (L < 768) {
;             int wgid = (L % 8) * 96 + L / 8;
;             const int gid = wgid / 192, rem = wgid % 192;
;             const int pm = gid * 8 + (rem % 8), pn = rem / 8;
;             u.a = H + (size_t)(256 + 256 * pm) * RB; u.b = WT + (size_t)(256 * pn) * RB; u.pm = pm; u.pn = pn;
;             u.kind = (pn < 8) ? 0 : ((pn >= 12 && pn < 20) ? 2 : 1);
.LBB0_331:
	s_add_i32 s60, s60, 1
	s_lshl_b32 s6, s60, 8
	s_add_i32 s6, s6, s2
	s_cmpk_lt_i32 s6, 0x300
	s_cselect_b64 s[38:39], -1, 0
	s_cmpk_gt_i32 s6, 0x2ff
	s_cbranch_scc1 .LBB0_333
	s_ashr_i32 s28, s6, 31
	s_lshr_b32 s28, s28, 29
	s_add_i32 s28, s6, s28
	s_ashr_i32 s29, s28, 3
	s_and_b32 s28, s28, 0x7fffff8
	s_sub_i32 s6, s6, s28
	s_mulk_i32 s6, 0x60
	s_add_i32 s6, s6, s29
	s_mul_hi_i32 s28, s6, 0x2aaaaaab
	s_lshr_b32 s29, s28, 31
	s_ashr_i32 s28, s28, 5
	s_add_i32 s28, s28, s29
	s_mul_i32 s29, s28, 0xc0
	s_sub_i32 s6, s6, s29
	s_lshr_b32 s29, s6, 5
	s_mul_i32 s29, s29, 3
	s_lshr_b32 s29, 0x2c298, s29
	s_and_b32 s29, s29, 7
	s_and_b32 s6, s6, 31
	s_lshl_b32 s29, s29, 5
	s_or_b32 s6, s6, s29
	s_sext_i32_i16 s29, s6
	s_bfe_u32 s29, s29, 0x3001c
	s_add_i32 s29, s6, s29
	s_sext_i32_i16 s34, s29
	s_and_b32 s29, s29, 0xfff8
	s_sub_i32 s29, s6, s29
	s_lshl_b32 s28, s28, 3
	s_sext_i32_i16 s29, s29
	s_add_i32 s62, s28, s29
	s_lshl_b32 s28, s62, 8
	s_ashr_i32 s29, s28, 31
	s_ashr_i32 s61, s34, 3
	s_lshl_b64 s[28:29], s[28:29], 12
	s_add_u32 s28, s52, s28
	s_addc_u32 s29, s53, s29
	s_add_u32 s34, s28, 0x100000
	s_addc_u32 s35, s29, 0
	s_lshl_b32 s28, s61, 8
	s_ashr_i32 s29, s28, 31
	s_lshl_b64 s[28:29], s[28:29], 12
	s_add_u32 s36, s54, s28
	s_addc_u32 s37, s55, s29
	s_add_i32 s28, s6, 0xffffffa0
	s_cmp_lt_u32 s28, 64
	s_cselect_b32 s28, 2, 1
	s_cmp_gt_i32 s6, 63
	s_cselect_b32 s63, s28, 0
